# phase 14 LN2: gamma/beta slices loaded once in front of the row loop (re-loads become v_mov), waits recomputed to cover only the row loads (no waiting on output stores)
# speedup vs baseline: 1.0065x; 1.0005x over previous
.LBB0_1616:
	s_cmp_lt_i32 s68, 15
	s_cselect_b64 s[6:7], -1, 0
	s_and_b64 s[4:5], s[6:7], s[4:5]
	s_andn2_b64 vcc, exec, s[4:5]
	s_cbranch_vccnz .LBB0_1620
	v_and_b32_e32 v0, 60, v206
	v_lshl_add_u32 v4, s2, 5, v0
	s_movk_i32 s2, 0x4000
	v_cmp_gt_i32_e32 vcc, s2, v4
	s_and_saveexec_b64 s[2:3], vcc
	s_cbranch_execz .LBB0_1620
	v_lshlrev_b32_e32 v0, 3, v1
	v_and_b32_e32 v5, 0x1f8, v0
	v_lshlrev_b32_e32 v0, 1, v5
	v_mov_b32_e32 v1, 0
	s_load_dwordx4 s[4:7], s[0:1], 0xe0
	v_lshl_add_u64 v[2:3], s[66:67], 0, v[0:1]
	s_mov_b64 s[0:1], 0x1c00000
	v_lshl_add_u64 v[6:7], v[2:3], 0, s[0:1]
	v_mbcnt_lo_u32_b32 v2, -1, 0
	v_mbcnt_hi_u32_b32 v2, -1, v2
	v_and_b32_e32 v3, 64, v2
	v_lshlrev_b32_e32 v0, 2, v5
	v_add_u32_e32 v3, 64, v3
	v_xor_b32_e32 v5, 32, v2
	v_cmp_lt_i32_e32 vcc, v5, v3
	s_waitcnt lgkmcnt(0)
	v_lshl_add_u64 v[8:9], s[4:5], 0, v[0:1]
	s_mov_b32 s4, 0x3727c5ac
	v_cndmask_b32_e32 v5, v2, v5, vcc
	v_lshlrev_b32_e32 v48, 2, v5
	v_xor_b32_e32 v5, 16, v2
	v_cmp_lt_i32_e32 vcc, v5, v3
	s_lshl_b32 s3, s70, 5
	v_lshl_add_u64 v[10:11], s[6:7], 0, v[0:1]
	v_cndmask_b32_e32 v5, v2, v5, vcc
	v_lshlrev_b32_e32 v49, 2, v5
	v_xor_b32_e32 v5, 8, v2
	v_cmp_lt_i32_e32 vcc, v5, v3
	v_lshl_add_u64 v[12:13], s[64:65], 0, v[0:1]
	s_mov_b64 s[0:1], 0
	v_cndmask_b32_e32 v5, v2, v5, vcc
	v_lshlrev_b32_e32 v50, 2, v5
	v_xor_b32_e32 v5, 4, v2
	v_cmp_lt_i32_e32 vcc, v5, v3
	s_mov_b32 s2, 0x3a800000
	v_mov_b64_e32 v[14:15], s[4:5]
	v_cndmask_b32_e32 v5, v2, v5, vcc
	v_lshlrev_b32_e32 v51, 2, v5
	v_xor_b32_e32 v5, 2, v2
	v_cmp_lt_i32_e32 vcc, v5, v3
	s_mov_b32 s4, 0x800000
	s_movk_i32 s5, 0x3fff
	v_cndmask_b32_e32 v5, v2, v5, vcc
	v_lshlrev_b32_e32 v52, 2, v5
	v_xor_b32_e32 v5, 1, v2
	v_cmp_lt_i32_e32 vcc, v5, v3
	s_nop 1
	v_cndmask_b32_e32 v2, v2, v5, vcc
	v_lshlrev_b32_e32 v53, 2, v2
	global_load_dwordx4 v[112:115], v[10:11], off
	global_load_dwordx4 v[116:119], v[10:11], off offset:16
	global_load_dwordx4 v[120:123], v[10:11], off offset:2048
	global_load_dwordx4 v[124:127], v[10:11], off offset:2064
	global_load_dwordx4 v[128:131], v[8:9], off
	global_load_dwordx4 v[132:135], v[8:9], off offset:16
	global_load_dwordx4 v[136:139], v[8:9], off offset:2048
	global_load_dwordx4 v[140:143], v[8:9], off offset:2064
	s_waitcnt vmcnt(0)
.LBB0_1619:
	v_ashrrev_i32_e32 v5, 31, v4
	v_lshlrev_b64 v[0:1], 11, v[4:5]
	v_add_u32_e32 v36, 1, v4
	v_lshl_add_u64 v[20:21], v[6:7], 0, v[0:1]
	v_ashrrev_i32_e32 v37, 31, v36
	global_load_dwordx4 v[0:3], v[20:21], off
	global_load_dwordx4 v[16:19], v[20:21], off offset:1024
	v_lshlrev_b64 v[20:21], 11, v[36:37]
	v_lshl_add_u64 v[28:29], v[6:7], 0, v[20:21]
	global_load_dwordx4 v[20:23], v[28:29], off
	global_load_dwordx4 v[24:27], v[28:29], off offset:1024
	v_mov_b32_e32 v54, v132
	v_mov_b32_e32 v55, v133
	v_mov_b32_e32 v56, v134
	v_mov_b32_e32 v57, v135
	v_mov_b32_e32 v58, v128
	v_mov_b32_e32 v59, v129
	v_mov_b32_e32 v60, v130
	v_mov_b32_e32 v61, v131
	v_mov_b32_e32 v62, v116
	v_mov_b32_e32 v63, v117
	v_mov_b32_e32 v64, v118
	v_mov_b32_e32 v65, v119
	v_mov_b32_e32 v66, v112
	v_mov_b32_e32 v67, v113
	v_mov_b32_e32 v68, v114
	v_mov_b32_e32 v69, v115
	v_lshlrev_b64 v[36:37], 12, v[36:37]
	v_lshl_add_u64 v[36:37], v[12:13], 0, v[36:37]
	s_waitcnt vmcnt(0)
	v_lshlrev_b32_e32 v30, 16, v0
	v_and_b32_e32 v31, 0xffff0000, v0
	v_add_f32_e32 v40, 0, v30
	v_lshlrev_b32_e32 v70, 16, v20
	v_lshlrev_b32_e32 v0, 16, v1
	v_and_b32_e32 v71, 0xffff0000, v20
	v_add_f32_e32 v40, v40, v31
	v_add_f32_e32 v41, 0, v70
	v_and_b32_e32 v1, 0xffff0000, v1
	v_lshlrev_b32_e32 v20, 16, v21
	v_add_f32_e32 v40, v40, v0
	v_add_f32_e32 v41, v41, v71
	v_lshlrev_b32_e32 v28, 16, v2
	v_and_b32_e32 v21, 0xffff0000, v21
	v_add_f32_e32 v40, v40, v1
	v_add_f32_e32 v41, v41, v20
	v_and_b32_e32 v29, 0xffff0000, v2
	v_lshlrev_b32_e32 v38, 16, v22
	v_add_f32_e32 v40, v40, v28
	v_add_f32_e32 v41, v41, v21
	v_lshlrev_b32_e32 v2, 16, v3
	v_and_b32_e32 v39, 0xffff0000, v22
	v_add_f32_e32 v40, v40, v29
	v_add_f32_e32 v41, v41, v38
	v_and_b32_e32 v3, 0xffff0000, v3
	v_lshlrev_b32_e32 v22, 16, v23
	v_add_f32_e32 v40, v40, v2
	v_add_f32_e32 v41, v41, v39
	v_lshlrev_b32_e32 v34, 16, v16
	v_and_b32_e32 v23, 0xffff0000, v23
	v_add_f32_e32 v40, v40, v3
	v_add_f32_e32 v41, v41, v22
	v_and_b32_e32 v35, 0xffff0000, v16
	v_lshlrev_b32_e32 v74, 16, v24
	v_add_f32_e32 v40, v40, v34
	v_add_f32_e32 v41, v41, v23
	v_lshlrev_b32_e32 v16, 16, v17
	v_and_b32_e32 v75, 0xffff0000, v24
	v_add_f32_e32 v40, v40, v35
	v_add_f32_e32 v41, v41, v74
	v_and_b32_e32 v17, 0xffff0000, v17
	v_lshlrev_b32_e32 v24, 16, v25
	v_add_f32_e32 v40, v40, v16
	v_add_f32_e32 v41, v41, v75
	v_lshlrev_b32_e32 v32, 16, v18
	v_and_b32_e32 v25, 0xffff0000, v25
	v_add_f32_e32 v40, v40, v17
	v_add_f32_e32 v41, v41, v24
	v_and_b32_e32 v33, 0xffff0000, v18
	v_lshlrev_b32_e32 v72, 16, v26
	v_add_f32_e32 v40, v40, v32
	v_add_f32_e32 v41, v41, v25
	v_lshlrev_b32_e32 v18, 16, v19
	v_and_b32_e32 v73, 0xffff0000, v26
	v_add_f32_e32 v40, v40, v33
	v_add_f32_e32 v41, v41, v72
	v_and_b32_e32 v19, 0xffff0000, v19
	v_lshlrev_b32_e32 v26, 16, v27
	v_add_f32_e32 v40, v40, v18
	v_add_f32_e32 v41, v41, v73
	v_and_b32_e32 v27, 0xffff0000, v27
	v_add_f32_e32 v40, v40, v19
	v_add_f32_e32 v41, v41, v26
	ds_bpermute_b32 v42, v48, v40
	v_add_f32_e32 v41, v41, v27
	ds_bpermute_b32 v43, v48, v41
	s_waitcnt lgkmcnt(1)
	v_add_f32_e32 v40, v40, v42
	ds_bpermute_b32 v42, v49, v40
	s_waitcnt lgkmcnt(1)
	v_add_f32_e32 v41, v41, v43
	ds_bpermute_b32 v43, v49, v41
	s_waitcnt lgkmcnt(1)
	v_add_f32_e32 v40, v40, v42
	ds_bpermute_b32 v42, v50, v40
	s_waitcnt lgkmcnt(1)
	v_add_f32_e32 v41, v41, v43
	ds_bpermute_b32 v43, v50, v41
	s_waitcnt lgkmcnt(1)
	v_add_f32_e32 v40, v40, v42
	ds_bpermute_b32 v42, v51, v40
	s_waitcnt lgkmcnt(1)
	v_add_f32_e32 v41, v41, v43
	ds_bpermute_b32 v43, v51, v41
	s_waitcnt lgkmcnt(1)
	v_add_f32_e32 v40, v40, v42
	ds_bpermute_b32 v42, v52, v40
	s_waitcnt lgkmcnt(1)
	v_add_f32_e32 v41, v41, v43
	ds_bpermute_b32 v43, v52, v41
	s_waitcnt lgkmcnt(1)
	v_add_f32_e32 v40, v40, v42
	ds_bpermute_b32 v42, v53, v40
	s_waitcnt lgkmcnt(1)
	v_add_f32_e32 v41, v41, v43
	ds_bpermute_b32 v43, v53, v41
	s_waitcnt lgkmcnt(1)
	v_add_f32_e32 v40, v40, v42
	v_mul_f32_e32 v46, 0x3a800000, v40
	s_waitcnt lgkmcnt(0)
	v_add_f32_e32 v76, v41, v43
	v_pk_add_f32 v[84:85], v[0:1], v[46:47] op_sel_hi:[1,0] neg_lo:[0,1] neg_hi:[0,1]
	v_mul_f32_e32 v0, 0x3a800000, v76
	v_pk_add_f32 v[82:83], v[30:31], v[46:47] op_sel_hi:[1,0] neg_lo:[0,1] neg_hi:[0,1]
	v_pk_add_f32 v[86:87], v[28:29], v[46:47] op_sel_hi:[1,0] neg_lo:[0,1] neg_hi:[0,1]
	v_pk_add_f32 v[28:29], v[70:71], v[0:1] op_sel_hi:[1,0] neg_lo:[0,1] neg_hi:[0,1]
	v_mov_b32_e32 v77, v83
	v_mov_b32_e32 v76, v29
	v_mov_b32_e32 v71, v82
	v_pk_add_f32 v[30:31], v[20:21], v[0:1] op_sel_hi:[1,0] neg_lo:[0,1] neg_hi:[0,1]
	v_mov_b32_e32 v70, v28
	v_pk_mul_f32 v[76:77], v[76:77], v[76:77]
	v_mov_b32_e32 v79, v84
	v_mov_b32_e32 v78, v30
	v_pk_fma_f32 v[70:71], v[70:71], v[70:71], v[76:77]
	v_pk_add_f32 v[40:41], v[34:35], v[46:47] op_sel_hi:[1,0] neg_lo:[0,1] neg_hi:[0,1]
	v_pk_add_f32 v[42:43], v[32:33], v[46:47] op_sel_hi:[1,0] neg_lo:[0,1] neg_hi:[0,1]
	v_pk_add_f32 v[32:33], v[38:39], v[0:1] op_sel_hi:[1,0] neg_lo:[0,1] neg_hi:[0,1]
	v_pk_add_f32 v[34:35], v[22:23], v[0:1] op_sel_hi:[1,0] neg_lo:[0,1] neg_hi:[0,1]
	v_pk_add_f32 v[22:23], v[24:25], v[0:1] op_sel_hi:[1,0] neg_lo:[0,1] neg_hi:[0,1]
	v_mov_b32_e32 v25, v85
	v_mov_b32_e32 v24, v31
	v_pk_fma_f32 v[70:71], v[78:79], v[78:79], v[70:71]
	v_mov_b32_e32 v39, v86
	v_mov_b32_e32 v38, v32
	v_pk_fma_f32 v[24:25], v[24:25], v[24:25], v[70:71]
	v_pk_add_f32 v[88:89], v[2:3], v[46:47] op_sel_hi:[1,0] neg_lo:[0,1] neg_hi:[0,1]
	v_pk_add_f32 v[20:21], v[72:73], v[0:1] op_sel_hi:[1,0] neg_lo:[0,1] neg_hi:[0,1]
	v_mov_b32_e32 v73, v87
	v_mov_b32_e32 v72, v33
	v_pk_fma_f32 v[24:25], v[38:39], v[38:39], v[24:25]
	v_pk_add_f32 v[44:45], v[16:17], v[46:47] op_sel_hi:[1,0] neg_lo:[0,1] neg_hi:[0,1]
	v_pk_add_f32 v[46:47], v[18:19], v[46:47] op_sel_hi:[1,0] neg_lo:[0,1] neg_hi:[0,1]
	v_pk_add_f32 v[18:19], v[74:75], v[0:1] op_sel_hi:[1,0] neg_lo:[0,1] neg_hi:[0,1]
	v_mov_b32_e32 v75, v88
	v_mov_b32_e32 v74, v34
	v_pk_fma_f32 v[24:25], v[72:73], v[72:73], v[24:25]
	v_mov_b32_e32 v81, v89
	v_mov_b32_e32 v80, v35
	v_pk_fma_f32 v[24:25], v[74:75], v[74:75], v[24:25]
	v_mov_b32_e32 v92, v18
	v_pk_fma_f32 v[24:25], v[80:81], v[80:81], v[24:25]
	v_mov_b32_e32 v93, v40
	v_pk_fma_f32 v[24:25], v[92:93], v[92:93], v[24:25]
	v_mov_b32_e32 v38, v19
	v_mov_b32_e32 v39, v41
	v_pk_fma_f32 v[24:25], v[38:39], v[38:39], v[24:25]
	v_mov_b32_e32 v38, v22
	v_mov_b32_e32 v39, v44
	v_pk_mul_f32 v[2:3], v[42:43], v[42:43]
	v_pk_mul_f32 v[90:91], v[20:21], v[20:21]
	v_pk_fma_f32 v[24:25], v[38:39], v[38:39], v[24:25]
	v_mov_b32_e32 v38, v23
	v_mov_b32_e32 v39, v45
	v_pk_fma_f32 v[24:25], v[38:39], v[38:39], v[24:25]
	v_mov_b32_e32 v38, v90
	v_mov_b32_e32 v39, v2
	v_pk_add_f32 v[26:27], v[26:27], v[0:1] op_sel_hi:[1,0] neg_lo:[0,1] neg_hi:[0,1]
	v_pk_mul_f32 v[16:17], v[46:47], v[46:47]
	v_pk_add_f32 v[24:25], v[38:39], v[24:25]
	v_pk_mul_f32 v[0:1], v[26:27], v[26:27]
	v_mov_b32_e32 v2, v91
	v_pk_add_f32 v[2:3], v[2:3], v[24:25]
	v_mov_b32_e32 v24, v0
	v_mov_b32_e32 v25, v16
	v_pk_add_f32 v[2:3], v[24:25], v[2:3]
	v_mov_b32_e32 v16, v1
	v_pk_add_f32 v[0:1], v[16:17], v[2:3]
	ds_bpermute_b32 v3, v48, v1
	ds_bpermute_b32 v2, v48, v0
	v_add_u32_e32 v24, 2, v4
	v_ashrrev_i32_e32 v25, 31, v24
	v_lshlrev_b64 v[16:17], 11, v[24:25]
	v_lshl_add_u64 v[16:17], v[6:7], 0, v[16:17]
	s_waitcnt lgkmcnt(0)
	v_pk_add_f32 v[0:1], v[0:1], v[2:3]
	ds_bpermute_b32 v3, v49, v1
	ds_bpermute_b32 v2, v49, v0
	global_load_dwordx4 v[70:73], v[16:17], off
	global_load_dwordx4 v[74:77], v[16:17], off offset:1024
	v_add_u32_e32 v16, 3, v4
	v_ashrrev_i32_e32 v17, 31, v16
	v_lshlrev_b64 v[38:39], 11, v[16:17]
	s_waitcnt lgkmcnt(0)
	v_pk_add_f32 v[0:1], v[0:1], v[2:3]
	ds_bpermute_b32 v3, v50, v1
	ds_bpermute_b32 v2, v50, v0
	v_lshl_add_u64 v[90:91], v[6:7], 0, v[38:39]
	v_lshlrev_b64 v[16:17], 12, v[16:17]
	s_waitcnt lgkmcnt(0)
	v_pk_add_f32 v[0:1], v[0:1], v[2:3]
	ds_bpermute_b32 v3, v51, v1
	ds_bpermute_b32 v2, v51, v0
	s_waitcnt lgkmcnt(0)
	v_pk_add_f32 v[0:1], v[0:1], v[2:3]
	ds_bpermute_b32 v3, v52, v1
	ds_bpermute_b32 v2, v52, v0
	s_waitcnt lgkmcnt(0)
	v_pk_add_f32 v[0:1], v[0:1], v[2:3]
	ds_bpermute_b32 v3, v53, v1
	ds_bpermute_b32 v2, v53, v0
	s_waitcnt lgkmcnt(0)
	v_pk_add_f32 v[0:1], v[0:1], v[2:3]
	s_nop 0
	v_pk_fma_f32 v[38:39], v[0:1], s[2:3], v[14:15] op_sel_hi:[1,0,0]
	s_nop 0
	v_mul_f32_e32 v0, 0x4b800000, v39
	v_cmp_gt_f32_e32 vcc, s4, v39
	s_nop 1
	v_cndmask_b32_e32 v0, v39, v0, vcc
	v_rsq_f32_e32 v39, v0
	global_load_dwordx4 v[78:81], v[90:91], off
	global_load_dwordx4 v[0:3], v[90:91], off offset:1024
	v_lshlrev_b64 v[90:91], 12, v[4:5]
	v_lshl_add_u64 v[90:91], v[12:13], 0, v[90:91]
	v_mul_f32_e32 v5, 0x45800000, v39
	v_cndmask_b32_e32 v92, v39, v5, vcc
	v_pk_mul_f32 v[82:83], v[82:83], v[92:93] op_sel_hi:[1,0]
	v_pk_mul_f32 v[84:85], v[84:85], v[92:93] op_sel_hi:[1,0]
	v_pk_fma_f32 v[58:59], v[58:59], v[82:83], v[66:67]
	v_pk_fma_f32 v[60:61], v[60:61], v[84:85], v[68:69]
	v_pk_mul_f32 v[66:67], v[86:87], v[92:93] op_sel_hi:[1,0]
	v_pk_mul_f32 v[68:69], v[88:89], v[92:93] op_sel_hi:[1,0]
	v_pk_fma_f32 v[54:55], v[54:55], v[66:67], v[62:63]
	v_pk_fma_f32 v[56:57], v[56:57], v[68:69], v[64:65]
	global_store_dwordx4 v[90:91], v[58:61], off
	global_store_dwordx4 v[90:91], v[54:57], off offset:16
	s_nop 1
	v_mov_b32_e32 v54, v120
	v_mov_b32_e32 v55, v121
	v_mov_b32_e32 v56, v122
	v_mov_b32_e32 v57, v123
	s_nop 0
	v_mov_b32_e32 v58, v136
	v_mov_b32_e32 v59, v137
	v_mov_b32_e32 v60, v138
	v_mov_b32_e32 v61, v139
	v_mov_b32_e32 v62, v140
	v_mov_b32_e32 v63, v141
	v_mov_b32_e32 v64, v142
	v_mov_b32_e32 v65, v143
	v_mov_b32_e32 v66, v124
	v_mov_b32_e32 v67, v125
	v_mov_b32_e32 v68, v126
	v_mov_b32_e32 v69, v127
	v_pk_mul_f32 v[44:45], v[44:45], v[92:93] op_sel_hi:[1,0]
	v_pk_mul_f32 v[40:41], v[40:41], v[92:93] op_sel_hi:[1,0]
	v_pk_mul_f32 v[46:47], v[46:47], v[92:93] op_sel_hi:[1,0]
	v_pk_mul_f32 v[84:85], v[42:43], v[92:93] op_sel_hi:[1,0]
	v_cmp_gt_f32_e32 vcc, s4, v38
	v_add_u32_e32 v4, s3, v4
	s_waitcnt vmcnt(5)
	v_lshlrev_b32_e32 v82, 16, v72
	v_and_b32_e32 v83, 0xffff0000, v72
	s_waitcnt vmcnt(4)
	v_lshlrev_b32_e32 v72, 16, v74
	s_waitcnt vmcnt(2)
	v_lshlrev_b32_e32 v92, 16, v1
	v_and_b32_e32 v93, 0xffff0000, v1
	v_lshlrev_b32_e32 v86, 16, v2
	v_and_b32_e32 v87, 0xffff0000, v2
	v_lshlrev_b32_e32 v88, 16, v3
	v_and_b32_e32 v89, 0xffff0000, v3
	s_waitcnt vmcnt(2)
	v_pk_fma_f32 v[40:41], v[58:59], v[40:41], v[54:55]
	v_pk_fma_f32 v[42:43], v[60:61], v[44:45], v[56:57]
	s_waitcnt vmcnt(2)
	v_pk_fma_f32 v[44:45], v[62:63], v[84:85], v[66:67]
	v_pk_fma_f32 v[46:47], v[64:65], v[46:47], v[68:69]
	global_store_dwordx4 v[90:91], v[40:43], off offset:2048
	global_store_dwordx4 v[90:91], v[44:47], off offset:2064
	s_nop 0
	v_mov_b32_e32 v40, v132
	v_mov_b32_e32 v41, v133
	v_mov_b32_e32 v42, v134
	v_mov_b32_e32 v43, v135
	s_nop 0
	v_mov_b32_e32 v44, v128
	v_mov_b32_e32 v45, v129
	v_mov_b32_e32 v46, v130
	v_mov_b32_e32 v47, v131
	v_mov_b32_e32 v54, v116
	v_mov_b32_e32 v55, v117
	v_mov_b32_e32 v56, v118
	v_mov_b32_e32 v57, v119
	v_mov_b32_e32 v58, v112
	v_mov_b32_e32 v59, v113
	v_mov_b32_e32 v60, v114
	v_mov_b32_e32 v61, v115
	v_lshlrev_b32_e32 v64, 16, v70
	v_and_b32_e32 v65, 0xffff0000, v70
	v_lshlrev_b32_e32 v90, 16, v0
	v_and_b32_e32 v91, 0xffff0000, v0
	v_add_f32_e32 v0, 0, v64
	v_lshlrev_b32_e32 v66, 16, v71
	v_add_f32_e32 v0, v0, v65
	v_and_b32_e32 v67, 0xffff0000, v71
	v_add_f32_e32 v0, v0, v66
	v_add_f32_e32 v0, v0, v67
	v_add_f32_e32 v0, v0, v82
	v_lshlrev_b32_e32 v62, 16, v73
	v_lshlrev_b32_e32 v84, 16, v78
	v_add_f32_e32 v0, v0, v83
	v_and_b32_e32 v63, 0xffff0000, v73
	v_and_b32_e32 v85, 0xffff0000, v78
	v_add_f32_e32 v1, 0, v84
	v_add_f32_e32 v0, v0, v62
	v_lshlrev_b32_e32 v78, 16, v79
	v_add_f32_e32 v1, v1, v85
	v_add_f32_e32 v0, v0, v63
	v_and_b32_e32 v73, 0xffff0000, v74
	v_and_b32_e32 v79, 0xffff0000, v79
	v_add_f32_e32 v1, v1, v78
	v_add_f32_e32 v0, v0, v72
	v_lshlrev_b32_e32 v68, 16, v76
	v_and_b32_e32 v69, 0xffff0000, v76
	v_lshlrev_b32_e32 v74, 16, v75
	v_lshlrev_b32_e32 v76, 16, v80
	v_add_f32_e32 v1, v1, v79
	v_add_f32_e32 v0, v0, v73
	v_lshlrev_b32_e32 v70, 16, v77
	v_and_b32_e32 v71, 0xffff0000, v77
	v_and_b32_e32 v75, 0xffff0000, v75
	v_and_b32_e32 v77, 0xffff0000, v80
	v_add_f32_e32 v1, v1, v76
	v_add_f32_e32 v0, v0, v74
	v_lshlrev_b32_e32 v80, 16, v81
	v_add_f32_e32 v1, v1, v77
	v_add_f32_e32 v0, v0, v75
	v_and_b32_e32 v81, 0xffff0000, v81
	v_add_f32_e32 v1, v1, v80
	v_add_f32_e32 v0, v0, v68
	v_add_f32_e32 v1, v1, v81
	v_add_f32_e32 v0, v0, v69
	v_add_f32_e32 v1, v1, v90
	v_add_f32_e32 v0, v0, v70
	v_add_f32_e32 v1, v1, v91
	v_add_f32_e32 v0, v0, v71
	v_add_f32_e32 v1, v1, v92
	ds_bpermute_b32 v2, v48, v0
	v_add_f32_e32 v1, v1, v93
	v_add_f32_e32 v1, v1, v86
	v_add_f32_e32 v1, v1, v87
	v_add_f32_e32 v1, v1, v88
	v_add_f32_e32 v1, v1, v89
	s_waitcnt lgkmcnt(0)
	v_add_f32_e32 v5, v0, v2
	v_mul_f32_e32 v0, 0x4b800000, v38
	ds_bpermute_b32 v3, v48, v1
	v_cndmask_b32_e32 v0, v38, v0, vcc
	v_rsq_f32_e32 v0, v0
	ds_bpermute_b32 v96, v49, v5
	s_waitcnt lgkmcnt(1)
	v_add_f32_e32 v95, v1, v3
	v_mul_f32_e32 v1, 0x45800000, v0
	v_cndmask_b32_e32 v94, v0, v1, vcc
	v_pk_mul_f32 v[2:3], v[30:31], v[94:95] op_sel_hi:[1,0]
	v_pk_mul_f32 v[0:1], v[28:29], v[94:95] op_sel_hi:[1,0]
	v_pk_mul_f32 v[30:31], v[34:35], v[94:95] op_sel_hi:[1,0]
	v_pk_mul_f32 v[28:29], v[32:33], v[94:95] op_sel_hi:[1,0]
	ds_bpermute_b32 v97, v49, v95
	v_pk_mul_f32 v[22:23], v[22:23], v[94:95] op_sel_hi:[1,0]
	v_pk_mul_f32 v[18:19], v[18:19], v[94:95] op_sel_hi:[1,0]
	v_pk_mul_f32 v[26:27], v[26:27], v[94:95] op_sel_hi:[1,0]
	s_waitcnt vmcnt(4)
	v_pk_fma_f32 v[28:29], v[40:41], v[28:29], v[54:55]
	s_waitcnt vmcnt(4)
	v_pk_fma_f32 v[0:1], v[44:45], v[0:1], v[58:59]
	v_pk_fma_f32 v[2:3], v[46:47], v[2:3], v[60:61]
	v_pk_fma_f32 v[30:31], v[42:43], v[30:31], v[56:57]
	global_store_dwordx4 v[36:37], v[0:3], off
	global_store_dwordx4 v[36:37], v[28:31], off offset:16
	v_mov_b32_e32 v32, v140
	v_mov_b32_e32 v33, v141
	v_mov_b32_e32 v34, v142
	v_mov_b32_e32 v35, v143
	v_mov_b32_e32 v38, v136
	v_mov_b32_e32 v39, v137
	v_mov_b32_e32 v40, v138
	v_mov_b32_e32 v41, v139
	v_mov_b32_e32 v42, v124
	v_mov_b32_e32 v43, v125
	v_mov_b32_e32 v44, v126
	v_mov_b32_e32 v45, v127
	v_mov_b32_e32 v54, v120
	v_mov_b32_e32 v55, v121
	v_mov_b32_e32 v56, v122
	v_mov_b32_e32 v57, v123
	s_waitcnt lgkmcnt(1)
	v_add_f32_e32 v0, v5, v96
	s_waitcnt lgkmcnt(0)
	v_add_f32_e32 v1, v95, v97
	ds_bpermute_b32 v2, v50, v0
	ds_bpermute_b32 v3, v50, v1
	v_pk_mul_f32 v[94:95], v[20:21], v[94:95] op_sel_hi:[1,0]
	s_waitcnt lgkmcnt(1)
	v_add_f32_e32 v0, v0, v2
	s_waitcnt lgkmcnt(0)
	v_add_f32_e32 v1, v1, v3
	ds_bpermute_b32 v2, v51, v0
	ds_bpermute_b32 v3, v51, v1
	s_waitcnt lgkmcnt(1)
	v_add_f32_e32 v0, v0, v2
	s_waitcnt lgkmcnt(0)
	v_add_f32_e32 v1, v1, v3
	ds_bpermute_b32 v2, v52, v0
	ds_bpermute_b32 v3, v52, v1
	s_waitcnt lgkmcnt(1)
	v_add_f32_e32 v0, v0, v2
	s_waitcnt lgkmcnt(0)
	v_add_f32_e32 v1, v1, v3
	ds_bpermute_b32 v2, v53, v0
	ds_bpermute_b32 v3, v53, v1
	s_waitcnt lgkmcnt(1)
	v_add_f32_e32 v0, v0, v2
	s_waitcnt lgkmcnt(0)
	v_add_f32_e32 v1, v1, v3
	v_mul_f32_e32 v0, 0x3a800000, v0
	v_mul_f32_e32 v30, 0x3a800000, v1
	v_pk_add_f32 v[46:47], v[64:65], v[0:1] op_sel_hi:[1,0] neg_lo:[0,1] neg_hi:[0,1]
	v_pk_add_f32 v[64:65], v[72:73], v[0:1] op_sel_hi:[1,0] neg_lo:[0,1] neg_hi:[0,1]
	v_pk_add_f32 v[72:73], v[84:85], v[30:31] op_sel_hi:[1,0] neg_lo:[0,1] neg_hi:[0,1]
	v_pk_add_f32 v[58:59], v[66:67], v[0:1] op_sel_hi:[1,0] neg_lo:[0,1] neg_hi:[0,1]
	v_pk_add_f32 v[60:61], v[82:83], v[0:1] op_sel_hi:[1,0] neg_lo:[0,1] neg_hi:[0,1]
	v_pk_add_f32 v[62:63], v[62:63], v[0:1] op_sel_hi:[1,0] neg_lo:[0,1] neg_hi:[0,1]
	v_pk_add_f32 v[66:67], v[74:75], v[0:1] op_sel_hi:[1,0] neg_lo:[0,1] neg_hi:[0,1]
	v_pk_add_f32 v[68:69], v[68:69], v[0:1] op_sel_hi:[1,0] neg_lo:[0,1] neg_hi:[0,1]
	v_pk_add_f32 v[70:71], v[70:71], v[0:1] op_sel_hi:[1,0] neg_lo:[0,1] neg_hi:[0,1]
	v_pk_add_f32 v[74:75], v[78:79], v[30:31] op_sel_hi:[1,0] neg_lo:[0,1] neg_hi:[0,1]
	v_pk_add_f32 v[76:77], v[76:77], v[30:31] op_sel_hi:[1,0] neg_lo:[0,1] neg_hi:[0,1]
	v_pk_add_f32 v[78:79], v[80:81], v[30:31] op_sel_hi:[1,0] neg_lo:[0,1] neg_hi:[0,1]
	v_pk_add_f32 v[0:1], v[90:91], v[30:31] op_sel_hi:[1,0] neg_lo:[0,1] neg_hi:[0,1]
	v_pk_add_f32 v[28:29], v[92:93], v[30:31] op_sel_hi:[1,0] neg_lo:[0,1] neg_hi:[0,1]
	v_pk_add_f32 v[2:3], v[86:87], v[30:31] op_sel_hi:[1,0] neg_lo:[0,1] neg_hi:[0,1]
	v_pk_add_f32 v[30:31], v[88:89], v[30:31] op_sel_hi:[1,0] neg_lo:[0,1] neg_hi:[0,1]
	v_mov_b32_e32 v86, v73
	v_mov_b32_e32 v87, v47
	v_pk_mul_f32 v[82:83], v[70:71], v[70:71]
	v_mov_b32_e32 v84, v72
	v_mov_b32_e32 v85, v46
	v_mov_b32_e32 v88, v74
	v_mov_b32_e32 v89, v58
	v_mov_b32_e32 v92, v75
	v_mov_b32_e32 v93, v59
	v_mov_b32_e32 v96, v76
	v_mov_b32_e32 v97, v60
	v_mov_b32_e32 v98, v77
	v_mov_b32_e32 v99, v61
	v_mov_b32_e32 v100, v78
	v_mov_b32_e32 v101, v62
	v_mov_b32_e32 v102, v79
	v_mov_b32_e32 v103, v63
	v_mov_b32_e32 v104, v0
	v_mov_b32_e32 v105, v64
	v_mov_b32_e32 v106, v1
	v_mov_b32_e32 v107, v65
	v_mov_b32_e32 v108, v28
	v_mov_b32_e32 v109, v66
	v_pk_mul_f32 v[80:81], v[68:69], v[68:69]
	v_pk_mul_f32 v[90:91], v[2:3], v[2:3]
	v_mov_b32_e32 v110, v29
	v_mov_b32_e32 v111, v67
	s_waitcnt vmcnt(6)
	v_pk_fma_f32 v[32:33], v[32:33], v[94:95], v[42:43]
	s_waitcnt vmcnt(6)
	v_pk_fma_f32 v[18:19], v[38:39], v[18:19], v[54:55]
	v_pk_fma_f32 v[20:21], v[40:41], v[22:23], v[56:57]
	v_pk_fma_f32 v[34:35], v[34:35], v[26:27], v[44:45]
	global_store_dwordx4 v[36:37], v[18:21], off offset:2048
	global_store_dwordx4 v[36:37], v[32:35], off offset:2064
	s_nop 0
	v_mov_b32_e32 v18, v132
	v_mov_b32_e32 v19, v133
	v_mov_b32_e32 v20, v134
	v_mov_b32_e32 v21, v135
	s_nop 0
	v_mov_b32_e32 v32, v128
	v_mov_b32_e32 v33, v129
	v_mov_b32_e32 v34, v130
	v_mov_b32_e32 v35, v131
	v_mov_b32_e32 v36, v116
	v_mov_b32_e32 v37, v117
	v_mov_b32_e32 v38, v118
	v_mov_b32_e32 v39, v119
	v_mov_b32_e32 v40, v112
	v_mov_b32_e32 v41, v113
	v_mov_b32_e32 v42, v114
	v_mov_b32_e32 v43, v115
	v_pk_mul_f32 v[22:23], v[30:31], v[30:31]
	v_pk_mul_f32 v[26:27], v[86:87], v[86:87]
	v_mov_b32_e32 v54, v22
	v_mov_b32_e32 v55, v82
	v_mov_b32_e32 v82, v23
	v_pk_fma_f32 v[22:23], v[84:85], v[84:85], v[26:27]
	v_mov_b32_e32 v44, v90
	v_pk_fma_f32 v[22:23], v[88:89], v[88:89], v[22:23]
	v_mov_b32_e32 v45, v80
	v_pk_fma_f32 v[22:23], v[92:93], v[92:93], v[22:23]
	v_mov_b32_e32 v80, v91
	v_pk_fma_f32 v[22:23], v[96:97], v[96:97], v[22:23]
	s_nop 0
	v_pk_fma_f32 v[22:23], v[98:99], v[98:99], v[22:23]
	s_nop 0
	v_pk_fma_f32 v[22:23], v[100:101], v[100:101], v[22:23]
	s_nop 0
	v_pk_fma_f32 v[22:23], v[102:103], v[102:103], v[22:23]
	s_nop 0
	v_pk_fma_f32 v[22:23], v[104:105], v[104:105], v[22:23]
	s_nop 0
	v_pk_fma_f32 v[22:23], v[106:107], v[106:107], v[22:23]
	s_nop 0
	v_pk_fma_f32 v[22:23], v[108:109], v[108:109], v[22:23]
	s_nop 0
	v_pk_fma_f32 v[22:23], v[110:111], v[110:111], v[22:23]
	s_nop 0
	v_pk_add_f32 v[22:23], v[44:45], v[22:23]
	s_nop 0
	v_pk_add_f32 v[22:23], v[80:81], v[22:23]
	s_nop 0
	v_pk_add_f32 v[22:23], v[54:55], v[22:23]
	s_nop 0
	v_pk_add_f32 v[22:23], v[82:83], v[22:23]
	ds_bpermute_b32 v27, v48, v23
	ds_bpermute_b32 v26, v48, v22
	s_waitcnt lgkmcnt(0)
	v_pk_add_f32 v[22:23], v[22:23], v[26:27]
	ds_bpermute_b32 v27, v49, v23
	ds_bpermute_b32 v26, v49, v22
	s_waitcnt lgkmcnt(0)
	v_pk_add_f32 v[22:23], v[22:23], v[26:27]
	ds_bpermute_b32 v27, v50, v23
	ds_bpermute_b32 v26, v50, v22
	s_waitcnt lgkmcnt(0)
	v_pk_add_f32 v[22:23], v[22:23], v[26:27]
	ds_bpermute_b32 v27, v51, v23
	ds_bpermute_b32 v26, v51, v22
	s_waitcnt lgkmcnt(0)
	v_pk_add_f32 v[22:23], v[22:23], v[26:27]
	ds_bpermute_b32 v27, v52, v23
	ds_bpermute_b32 v26, v52, v22
	s_waitcnt lgkmcnt(0)
	v_pk_add_f32 v[22:23], v[22:23], v[26:27]
	ds_bpermute_b32 v27, v53, v23
	ds_bpermute_b32 v26, v53, v22
	s_waitcnt lgkmcnt(0)
	v_pk_add_f32 v[22:23], v[22:23], v[26:27]
	s_nop 0
	v_pk_fma_f32 v[26:27], v[22:23], s[2:3], v[14:15] op_sel_hi:[1,0,0]
	v_lshlrev_b64 v[22:23], 12, v[24:25]
	v_mul_f32_e32 v5, 0x4b800000, v27
	v_cmp_gt_f32_e32 vcc, s4, v27
	v_lshl_add_u64 v[44:45], v[12:13], 0, v[22:23]
	s_nop 0
	v_cndmask_b32_e32 v5, v27, v5, vcc
	v_rsq_f32_e32 v5, v5
	s_nop 0
	v_mul_f32_e32 v22, 0x45800000, v5
	v_cndmask_b32_e32 v54, v5, v22, vcc
	v_pk_mul_f32 v[24:25], v[58:59], v[54:55] op_sel_hi:[1,0]
	v_pk_mul_f32 v[22:23], v[46:47], v[54:55] op_sel_hi:[1,0]
	v_pk_mul_f32 v[46:47], v[62:63], v[54:55] op_sel_hi:[1,0]
	v_pk_mul_f32 v[56:57], v[60:61], v[54:55] op_sel_hi:[1,0]
	s_waitcnt vmcnt(8)
	v_pk_fma_f32 v[22:23], v[32:33], v[22:23], v[40:41]
	v_pk_fma_f32 v[24:25], v[34:35], v[24:25], v[42:43]
	v_pk_fma_f32 v[18:19], v[18:19], v[56:57], v[36:37]
	v_pk_fma_f32 v[20:21], v[20:21], v[46:47], v[38:39]
	global_store_dwordx4 v[44:45], v[22:25], off
	global_store_dwordx4 v[44:45], v[18:21], off offset:16
	s_nop 1
	v_mov_b32_e32 v18, v120
	v_mov_b32_e32 v19, v121
	v_mov_b32_e32 v20, v122
	v_mov_b32_e32 v21, v123
	s_nop 0
	v_mov_b32_e32 v22, v136
	v_mov_b32_e32 v23, v137
	v_mov_b32_e32 v24, v138
	v_mov_b32_e32 v25, v139
	v_mov_b32_e32 v32, v140
	v_mov_b32_e32 v33, v141
	v_mov_b32_e32 v34, v142
	v_mov_b32_e32 v35, v143
	v_mov_b32_e32 v36, v124
	v_mov_b32_e32 v37, v125
	v_mov_b32_e32 v38, v126
	v_mov_b32_e32 v39, v127
	v_pk_mul_f32 v[40:41], v[66:67], v[54:55] op_sel_hi:[1,0]
	v_pk_mul_f32 v[42:43], v[64:65], v[54:55] op_sel_hi:[1,0]
	v_pk_mul_f32 v[46:47], v[70:71], v[54:55] op_sel_hi:[1,0]
	v_pk_mul_f32 v[54:55], v[68:69], v[54:55] op_sel_hi:[1,0]
	v_mul_f32_e32 v5, 0x4b800000, v26
	v_cmp_gt_f32_e32 vcc, s4, v26
	s_waitcnt vmcnt(10)
	v_pk_fma_f32 v[18:19], v[22:23], v[42:43], v[18:19]
	v_pk_fma_f32 v[20:21], v[24:25], v[40:41], v[20:21]
	s_waitcnt vmcnt(10)
	v_pk_fma_f32 v[22:23], v[32:33], v[54:55], v[36:37]
	v_pk_fma_f32 v[24:25], v[34:35], v[46:47], v[38:39]
	global_store_dwordx4 v[44:45], v[18:21], off offset:2048
	global_store_dwordx4 v[44:45], v[22:25], off offset:2064
	s_nop 0
	v_mov_b32_e32 v18, v112
	v_mov_b32_e32 v19, v113
	v_mov_b32_e32 v20, v114
	v_mov_b32_e32 v21, v115
	s_nop 0
	v_mov_b32_e32 v22, v128
	v_mov_b32_e32 v23, v129
	v_mov_b32_e32 v24, v130
	v_mov_b32_e32 v25, v131
	v_mov_b32_e32 v32, v132
	v_mov_b32_e32 v33, v133
	v_mov_b32_e32 v34, v134
	v_mov_b32_e32 v35, v135
	v_mov_b32_e32 v36, v116
	v_mov_b32_e32 v37, v117
	v_mov_b32_e32 v38, v118
	v_mov_b32_e32 v39, v119
	v_cndmask_b32_e32 v5, v26, v5, vcc
	v_rsq_f32_e32 v5, v5
	v_lshl_add_u64 v[40:41], v[12:13], 0, v[16:17]
	v_mul_f32_e32 v16, 0x45800000, v5
	v_cndmask_b32_e32 v42, v5, v16, vcc
	v_pk_mul_f32 v[26:27], v[74:75], v[42:43] op_sel_hi:[1,0]
	v_pk_mul_f32 v[16:17], v[72:73], v[42:43] op_sel_hi:[1,0]
	v_pk_mul_f32 v[44:45], v[78:79], v[42:43] op_sel_hi:[1,0]
	v_pk_mul_f32 v[46:47], v[76:77], v[42:43] op_sel_hi:[1,0]
	v_cmp_lt_i32_e32 vcc, s5, v4
	v_pk_mul_f32 v[28:29], v[28:29], v[42:43] op_sel_hi:[1,0]
	v_pk_mul_f32 v[0:1], v[0:1], v[42:43] op_sel_hi:[1,0]
	s_or_b64 s[0:1], vcc, s[0:1]
	v_pk_mul_f32 v[30:31], v[30:31], v[42:43] op_sel_hi:[1,0]
	s_waitcnt vmcnt(12)
	v_pk_fma_f32 v[16:17], v[22:23], v[16:17], v[18:19]
	v_pk_fma_f32 v[18:19], v[24:25], v[26:27], v[20:21]
	s_waitcnt vmcnt(12)
	v_pk_fma_f32 v[20:21], v[32:33], v[46:47], v[36:37]
	v_pk_fma_f32 v[22:23], v[34:35], v[44:45], v[38:39]
	global_store_dwordx4 v[40:41], v[16:19], off
	global_store_dwordx4 v[40:41], v[20:23], off offset:16
	s_nop 0
	v_mov_b32_e32 v16, v120
	v_mov_b32_e32 v17, v121
	v_mov_b32_e32 v18, v122
	v_mov_b32_e32 v19, v123
	s_nop 0
	v_mov_b32_e32 v20, v136
	v_mov_b32_e32 v21, v137
	v_mov_b32_e32 v22, v138
	v_mov_b32_e32 v23, v139
	v_mov_b32_e32 v24, v140
	v_mov_b32_e32 v25, v141
	v_mov_b32_e32 v26, v142
	v_mov_b32_e32 v27, v143
	v_mov_b32_e32 v32, v124
	v_mov_b32_e32 v33, v125
	v_mov_b32_e32 v34, v126
	v_mov_b32_e32 v35, v127
	v_pk_mul_f32 v[36:37], v[2:3], v[42:43] op_sel_hi:[1,0]
	s_waitcnt vmcnt(14)
	v_pk_fma_f32 v[0:1], v[20:21], v[0:1], v[16:17]
	v_pk_fma_f32 v[2:3], v[22:23], v[28:29], v[18:19]
	s_waitcnt vmcnt(14)
	v_pk_fma_f32 v[16:17], v[24:25], v[36:37], v[32:33]
	v_pk_fma_f32 v[18:19], v[26:27], v[30:31], v[34:35]
	global_store_dwordx4 v[40:41], v[0:3], off offset:2048
	global_store_dwordx4 v[40:41], v[16:19], off offset:2064
	s_andn2_b64 exec, exec, s[0:1]
	s_cbranch_execnz .LBB0_1619
